# P0 load rebalance: the 1024 mem->bf16+rstd rows are done by workgroups 128-255 (which have one transposer item fewer) instead of workgroups 0-127
# baseline (speedup 1.0000x reference)
.LBB0_205:
	s_or_b64 exec, exec, s[14:15]
	s_cmpk_lg_u32 s88, 0x100
	s_cbranch_scc1 .Lmy_mem_keep
	v_subrev_u32_e32 v64, 0x400, v64
	v_ashrrev_i32_e32 v65, 31, v64
.Lmy_mem_keep:
	s_movk_i32 s0, 0x400
	v_cmp_gt_u32_e32 vcc, s0, v64
	s_and_saveexec_b64 s[2:3], vcc
	s_cbranch_execz .LBB0_210
	v_mbcnt_lo_u32_b32 v0, -1, 0
	v_mbcnt_hi_u32_b32 v0, -1, v0
	v_and_b32_e32 v1, 64, v0
	v_add_u32_e32 v1, 64, v1
	v_xor_b32_e32 v2, 1, v0
	v_cmp_lt_i32_e32 vcc, v2, v1
	s_ashr_i32 s13, s12, 31
	s_mov_b64 s[0:1], 0x1000
	v_cndmask_b32_e32 v2, v0, v2, vcc
	v_lshlrev_b32_e32 v6, 2, v2
	v_xor_b32_e32 v2, 2, v0
	v_cmp_lt_i32_e32 vcc, v2, v1
	v_lshlrev_b64 v[4:5], 12, v[64:65]
	s_lshl_b64 s[4:5], s[12:13], 2
	v_cndmask_b32_e32 v2, v0, v2, vcc
	v_lshlrev_b32_e32 v7, 2, v2
	v_xor_b32_e32 v2, 4, v0
	v_cmp_lt_i32_e32 vcc, v2, v1
	s_lshl_b64 s[6:7], s[12:13], 13
	v_lshl_or_b32 v4, v93, 3, v4
	v_cndmask_b32_e32 v2, v0, v2, vcc
	v_lshlrev_b32_e32 v8, 2, v2
	v_xor_b32_e32 v2, 8, v0
	v_cmp_lt_i32_e32 vcc, v2, v1
	s_lshl_b64 s[8:9], s[12:13], 12
	s_mov_b64 s[10:11], 0
	v_cndmask_b32_e32 v2, v0, v2, vcc
	v_lshlrev_b32_e32 v9, 2, v2
	v_xor_b32_e32 v2, 16, v0
	v_cmp_lt_i32_e32 vcc, v2, v1
	s_mov_b32 s13, 0x5300000
	v_mov_b32_e32 v12, 0x358637bd
	v_cndmask_b32_e32 v2, v0, v2, vcc
	v_lshlrev_b32_e32 v10, 2, v2
	v_xor_b32_e32 v2, 32, v0
	v_cmp_lt_i32_e32 vcc, v2, v1
	s_mov_b32 s16, 0x800000
	s_movk_i32 s17, 0x3ff
	v_cndmask_b32_e32 v0, v0, v2, vcc
	s_waitcnt lgkmcnt(0)
	v_lshlrev_b64 v[2:3], 13, v[64:65]
	v_lshl_or_b32 v2, v93, 4, v2
	v_lshlrev_b32_e32 v11, 2, v0
	v_mov_b64_e32 v[0:1], 0x5088000
	v_lshl_add_u64 v[2:3], s[50:51], 0, v[2:3]
	v_cmp_eq_u32_e32 vcc, 0, v93
	v_lshl_add_u64 v[0:1], v[64:65], 2, v[0:1]
	v_lshl_add_u64 v[2:3], v[2:3], 0, s[0:1]
	s_branch .LBB0_208
